# nt cache hint also on P1/P9 (SwiGLU up GEMM) epilogue stores
# baseline (speedup 1.0000x reference)
.LBB0_89:
	v_mul_f32_e32 v146, 0xbfb8aa3b, v126
	v_exp_f32_e32 v146, v146
	v_mul_f32_e32 v147, 0xbfb8aa3b, v127
	v_exp_f32_e32 v147, v147
	v_lshl_or_b32 v154, s51, 7, v149
	v_add_f32_e32 v146, 1.0, v146
	v_rcp_f32_e32 v156, v146
	v_add_f32_e32 v146, 1.0, v147
	v_rcp_f32_e32 v157, v146
	v_lshl_add_u32 v153, s26, 8, v1
	v_ashrrev_i32_e32 v155, 31, v154
	v_mov_b64_e32 v[146:147], s[6:7]
	v_pk_mul_f32 v[126:127], v[126:127], v[156:157]
	v_mul_f32_e32 v156, 0xbfb8aa3b, v128
	v_mul_f32_e32 v157, 0xbfb8aa3b, v129
	v_exp_f32_e32 v156, v156
	v_exp_f32_e32 v157, v157
	v_pk_mul_f32 v[118:119], v[126:127], v[118:119]
	v_mad_i64_i32 v[158:159], s[20:21], v153, s50, v[146:147]
	v_add_f32_e32 v126, 1.0, v156
	v_add_f32_e32 v127, 1.0, v157
	v_mul_f32_e32 v156, 0xbfb8aa3b, v122
	v_mul_f32_e32 v157, 0xbfb8aa3b, v123
	v_rcp_f32_e32 v126, v126
	v_rcp_f32_e32 v127, v127
	v_exp_f32_e32 v156, v156
	v_exp_f32_e32 v157, v157
	s_andn2_b64 vcc, exec, s[2:3]
	v_pk_mul_f32 v[126:127], v[128:129], v[126:127]
	v_add_f32_e32 v128, 1.0, v156
	v_add_f32_e32 v129, 1.0, v157
	v_mul_f32_e32 v156, 0xbfb8aa3b, v124
	v_mul_f32_e32 v157, 0xbfb8aa3b, v125
	v_exp_f32_e32 v156, v156
	v_exp_f32_e32 v157, v157
	v_rcp_f32_e32 v128, v128
	v_rcp_f32_e32 v129, v129
	v_add_f32_e32 v156, 1.0, v156
	v_add_f32_e32 v157, 1.0, v157
	v_rcp_f32_e32 v156, v156
	v_rcp_f32_e32 v157, v157
	v_pk_mul_f32 v[122:123], v[122:123], v[128:129]
	v_pk_mul_f32 v[120:121], v[126:127], v[120:121]
	v_pk_mul_f32 v[122:123], v[122:123], v[114:115]
	v_pk_mul_f32 v[114:115], v[124:125], v[156:157]
	s_mov_b64 s[2:3], -1
	v_pk_mul_f32 v[124:125], v[114:115], v[116:117]
	v_cvt_pk_bf16_f32 v117, v120, v121
	v_mul_f32_e32 v120, 0xbfb8aa3b, v110
	v_mul_f32_e32 v121, 0xbfb8aa3b, v111
	v_exp_f32_e32 v120, v120
	v_exp_f32_e32 v121, v121
	v_lshlrev_b64 v[114:115], 1, v[154:155]
	v_lshl_add_u64 v[126:127], v[158:159], 0, v[114:115]
	v_cvt_pk_bf16_f32 v116, v118, v119
	v_cvt_pk_bf16_f32 v118, v122, v123
	v_cvt_pk_bf16_f32 v119, v124, v125
	global_store_dwordx4 v[126:127], v[116:119], off nt
	s_nop 1
	v_add_f32_e32 v116, 1.0, v120
	v_add_f32_e32 v117, 1.0, v121
	v_rcp_f32_e32 v116, v116
	v_rcp_f32_e32 v117, v117
	v_or_b32_e32 v118, 16, v153
	v_mad_i64_i32 v[118:119], s[20:21], v118, s50, v[146:147]
	v_pk_mul_f32 v[110:111], v[110:111], v[116:117]
	v_mul_f32_e32 v116, 0xbfb8aa3b, v112
	v_mul_f32_e32 v117, 0xbfb8aa3b, v113
	v_exp_f32_e32 v116, v116
	v_exp_f32_e32 v117, v117
	v_pk_mul_f32 v[102:103], v[110:111], v[102:103]
	v_add_f32_e32 v110, 1.0, v116
	v_add_f32_e32 v111, 1.0, v117
	v_mul_f32_e32 v116, 0xbfb8aa3b, v106
	v_mul_f32_e32 v117, 0xbfb8aa3b, v107
	v_rcp_f32_e32 v110, v110
	v_rcp_f32_e32 v111, v111
	v_exp_f32_e32 v116, v116
	v_exp_f32_e32 v117, v117
	v_pk_mul_f32 v[110:111], v[112:113], v[110:111]
	v_add_f32_e32 v112, 1.0, v116
	v_add_f32_e32 v113, 1.0, v117
	v_mul_f32_e32 v116, 0xbfb8aa3b, v108
	v_mul_f32_e32 v117, 0xbfb8aa3b, v109
	v_exp_f32_e32 v116, v116
	v_exp_f32_e32 v117, v117
	v_rcp_f32_e32 v112, v112
	v_rcp_f32_e32 v113, v113
	v_add_f32_e32 v116, 1.0, v116
	v_add_f32_e32 v117, 1.0, v117
	v_rcp_f32_e32 v116, v116
	v_rcp_f32_e32 v117, v117
	v_pk_mul_f32 v[106:107], v[106:107], v[112:113]
	v_pk_mul_f32 v[104:105], v[110:111], v[104:105]
	v_pk_mul_f32 v[106:107], v[106:107], v[98:99]
	v_pk_mul_f32 v[98:99], v[108:109], v[116:117]
	v_lshl_add_u64 v[110:111], v[118:119], 0, v[114:115]
	v_pk_mul_f32 v[108:109], v[98:99], v[100:101]
	v_cvt_pk_bf16_f32 v98, v102, v103
	v_mul_f32_e32 v102, 0xbfb8aa3b, v94
	v_mul_f32_e32 v103, 0xbfb8aa3b, v95
	v_exp_f32_e32 v102, v102
	v_exp_f32_e32 v103, v103
	v_cvt_pk_bf16_f32 v99, v104, v105
	v_cvt_pk_bf16_f32 v100, v106, v107
	v_cvt_pk_bf16_f32 v101, v108, v109
	global_store_dwordx4 v[110:111], v[98:101], off nt
	s_nop 1
	v_add_f32_e32 v98, 1.0, v102
	v_add_f32_e32 v99, 1.0, v103
	v_rcp_f32_e32 v98, v98
	v_rcp_f32_e32 v99, v99
	v_or_b32_e32 v100, 32, v153
	v_mad_i64_i32 v[100:101], s[20:21], v100, s50, v[146:147]
	v_pk_mul_f32 v[94:95], v[94:95], v[98:99]
	v_mul_f32_e32 v98, 0xbfb8aa3b, v96
	v_mul_f32_e32 v99, 0xbfb8aa3b, v97
	v_exp_f32_e32 v98, v98
	v_exp_f32_e32 v99, v99
	v_pk_mul_f32 v[86:87], v[94:95], v[86:87]
	v_add_f32_e32 v94, 1.0, v98
	v_add_f32_e32 v95, 1.0, v99
	v_mul_f32_e32 v98, 0xbfb8aa3b, v90
	v_mul_f32_e32 v99, 0xbfb8aa3b, v91
	v_rcp_f32_e32 v94, v94
	v_rcp_f32_e32 v95, v95
	v_exp_f32_e32 v98, v98
	v_exp_f32_e32 v99, v99
	v_pk_mul_f32 v[94:95], v[96:97], v[94:95]
	v_add_f32_e32 v96, 1.0, v98
	v_add_f32_e32 v97, 1.0, v99
	v_mul_f32_e32 v98, 0xbfb8aa3b, v92
	v_mul_f32_e32 v99, 0xbfb8aa3b, v93
	v_exp_f32_e32 v98, v98
	v_exp_f32_e32 v99, v99
	v_rcp_f32_e32 v96, v96
	v_rcp_f32_e32 v97, v97
	v_add_f32_e32 v98, 1.0, v98
	v_add_f32_e32 v99, 1.0, v99
	v_rcp_f32_e32 v98, v98
	v_rcp_f32_e32 v99, v99
	v_pk_mul_f32 v[90:91], v[90:91], v[96:97]
	v_pk_mul_f32 v[88:89], v[94:95], v[88:89]
	v_pk_mul_f32 v[90:91], v[90:91], v[82:83]
	v_pk_mul_f32 v[82:83], v[92:93], v[98:99]
	v_lshl_add_u64 v[94:95], v[100:101], 0, v[114:115]
	v_pk_mul_f32 v[92:93], v[82:83], v[84:85]
	v_cvt_pk_bf16_f32 v82, v86, v87
	v_mul_f32_e32 v86, 0xbfb8aa3b, v78
	v_mul_f32_e32 v87, 0xbfb8aa3b, v79
	v_exp_f32_e32 v86, v86
	v_exp_f32_e32 v87, v87
	v_cvt_pk_bf16_f32 v83, v88, v89
	v_cvt_pk_bf16_f32 v84, v90, v91
	v_cvt_pk_bf16_f32 v85, v92, v93
	global_store_dwordx4 v[94:95], v[82:85], off nt
	s_nop 1
	v_add_f32_e32 v82, 1.0, v86
	v_add_f32_e32 v83, 1.0, v87
	v_rcp_f32_e32 v82, v82
	v_rcp_f32_e32 v83, v83
	v_or_b32_e32 v84, 48, v153
	v_mad_i64_i32 v[84:85], s[20:21], v84, s50, v[146:147]
	v_pk_mul_f32 v[78:79], v[78:79], v[82:83]
	v_mul_f32_e32 v82, 0xbfb8aa3b, v80
	v_mul_f32_e32 v83, 0xbfb8aa3b, v81
	v_exp_f32_e32 v82, v82
	v_exp_f32_e32 v83, v83
	v_pk_mul_f32 v[70:71], v[78:79], v[70:71]
	v_add_f32_e32 v78, 1.0, v82
	v_add_f32_e32 v79, 1.0, v83
	v_mul_f32_e32 v82, 0xbfb8aa3b, v74
	v_mul_f32_e32 v83, 0xbfb8aa3b, v75
	v_rcp_f32_e32 v78, v78
	v_rcp_f32_e32 v79, v79
	v_exp_f32_e32 v82, v82
	v_exp_f32_e32 v83, v83
	v_pk_mul_f32 v[78:79], v[80:81], v[78:79]
	v_add_f32_e32 v80, 1.0, v82
	v_add_f32_e32 v81, 1.0, v83
	v_mul_f32_e32 v82, 0xbfb8aa3b, v76
	v_mul_f32_e32 v83, 0xbfb8aa3b, v77
	v_exp_f32_e32 v82, v82
	v_exp_f32_e32 v83, v83
	v_rcp_f32_e32 v80, v80
	v_rcp_f32_e32 v81, v81
	v_add_f32_e32 v82, 1.0, v82
	v_add_f32_e32 v83, 1.0, v83
	v_rcp_f32_e32 v82, v82
	v_rcp_f32_e32 v83, v83
	v_pk_mul_f32 v[74:75], v[74:75], v[80:81]
	v_pk_mul_f32 v[72:73], v[78:79], v[72:73]
	v_pk_mul_f32 v[74:75], v[74:75], v[66:67]
	v_pk_mul_f32 v[66:67], v[76:77], v[82:83]
	v_lshl_add_u64 v[78:79], v[84:85], 0, v[114:115]
	v_pk_mul_f32 v[76:77], v[66:67], v[68:69]
	v_cvt_pk_bf16_f32 v66, v70, v71
	v_mul_f32_e32 v70, 0xbfb8aa3b, v62
	v_mul_f32_e32 v71, 0xbfb8aa3b, v63
	v_exp_f32_e32 v70, v70
	v_exp_f32_e32 v71, v71
	v_cvt_pk_bf16_f32 v67, v72, v73
	v_cvt_pk_bf16_f32 v68, v74, v75
	v_cvt_pk_bf16_f32 v69, v76, v77
	global_store_dwordx4 v[78:79], v[66:69], off nt
	s_nop 1
	v_add_f32_e32 v66, 1.0, v70
	v_add_f32_e32 v67, 1.0, v71
	v_rcp_f32_e32 v66, v66
	v_rcp_f32_e32 v67, v67
	v_add_u32_e32 v68, 0x80, v153
	v_mad_i64_i32 v[68:69], s[20:21], v68, s50, v[146:147]
	v_pk_mul_f32 v[62:63], v[62:63], v[66:67]
	v_mul_f32_e32 v66, 0xbfb8aa3b, v64
	v_mul_f32_e32 v67, 0xbfb8aa3b, v65
	v_exp_f32_e32 v66, v66
	v_exp_f32_e32 v67, v67
	v_pk_mul_f32 v[54:55], v[62:63], v[54:55]
	v_add_f32_e32 v62, 1.0, v66
	v_add_f32_e32 v63, 1.0, v67
	v_mul_f32_e32 v66, 0xbfb8aa3b, v58
	v_mul_f32_e32 v67, 0xbfb8aa3b, v59
	v_rcp_f32_e32 v62, v62
	v_rcp_f32_e32 v63, v63
	v_exp_f32_e32 v66, v66
	v_exp_f32_e32 v67, v67
	v_pk_mul_f32 v[62:63], v[64:65], v[62:63]
	v_add_f32_e32 v64, 1.0, v66
	v_add_f32_e32 v65, 1.0, v67
	v_mul_f32_e32 v66, 0xbfb8aa3b, v60
	v_mul_f32_e32 v67, 0xbfb8aa3b, v61
	v_exp_f32_e32 v66, v66
	v_exp_f32_e32 v67, v67
	v_rcp_f32_e32 v64, v64
	v_rcp_f32_e32 v65, v65
	v_add_f32_e32 v66, 1.0, v66
	v_add_f32_e32 v67, 1.0, v67
	v_rcp_f32_e32 v66, v66
	v_rcp_f32_e32 v67, v67
	v_pk_mul_f32 v[58:59], v[58:59], v[64:65]
	v_pk_mul_f32 v[56:57], v[62:63], v[56:57]
	v_pk_mul_f32 v[58:59], v[58:59], v[50:51]
	v_pk_mul_f32 v[50:51], v[60:61], v[66:67]
	v_lshl_add_u64 v[62:63], v[68:69], 0, v[114:115]
	v_pk_mul_f32 v[60:61], v[50:51], v[52:53]
	v_cvt_pk_bf16_f32 v50, v54, v55
	v_mul_f32_e32 v54, 0xbfb8aa3b, v46
	v_mul_f32_e32 v55, 0xbfb8aa3b, v47
	v_exp_f32_e32 v54, v54
	v_exp_f32_e32 v55, v55
	v_cvt_pk_bf16_f32 v51, v56, v57
	v_cvt_pk_bf16_f32 v52, v58, v59
	v_cvt_pk_bf16_f32 v53, v60, v61
	global_store_dwordx4 v[62:63], v[50:53], off nt
	s_nop 1
	v_add_f32_e32 v50, 1.0, v54
	v_add_f32_e32 v51, 1.0, v55
	v_rcp_f32_e32 v50, v50
	v_rcp_f32_e32 v51, v51
	v_add_u32_e32 v52, 0x90, v153
	v_mad_i64_i32 v[52:53], s[20:21], v52, s50, v[146:147]
	v_pk_mul_f32 v[46:47], v[46:47], v[50:51]
	v_mul_f32_e32 v50, 0xbfb8aa3b, v48
	v_mul_f32_e32 v51, 0xbfb8aa3b, v49
	v_exp_f32_e32 v50, v50
	v_exp_f32_e32 v51, v51
	v_pk_mul_f32 v[38:39], v[46:47], v[38:39]
	v_add_f32_e32 v46, 1.0, v50
	v_add_f32_e32 v47, 1.0, v51
	v_mul_f32_e32 v50, 0xbfb8aa3b, v42
	v_mul_f32_e32 v51, 0xbfb8aa3b, v43
	v_rcp_f32_e32 v46, v46
	v_rcp_f32_e32 v47, v47
	v_exp_f32_e32 v50, v50
	v_exp_f32_e32 v51, v51
	v_pk_mul_f32 v[46:47], v[48:49], v[46:47]
	v_add_f32_e32 v48, 1.0, v50
	v_add_f32_e32 v49, 1.0, v51
	v_mul_f32_e32 v50, 0xbfb8aa3b, v44
	v_mul_f32_e32 v51, 0xbfb8aa3b, v45
	v_exp_f32_e32 v50, v50
	v_exp_f32_e32 v51, v51
	v_rcp_f32_e32 v48, v48
	v_rcp_f32_e32 v49, v49
	v_add_f32_e32 v50, 1.0, v50
	v_add_f32_e32 v51, 1.0, v51
	v_rcp_f32_e32 v50, v50
	v_rcp_f32_e32 v51, v51
	v_pk_mul_f32 v[42:43], v[42:43], v[48:49]
	v_pk_mul_f32 v[40:41], v[46:47], v[40:41]
	v_pk_mul_f32 v[42:43], v[42:43], v[34:35]
	v_pk_mul_f32 v[34:35], v[44:45], v[50:51]
	v_lshl_add_u64 v[46:47], v[52:53], 0, v[114:115]
	v_pk_mul_f32 v[44:45], v[34:35], v[36:37]
	v_cvt_pk_bf16_f32 v34, v38, v39
	v_mul_f32_e32 v38, 0xbfb8aa3b, v30
	v_mul_f32_e32 v39, 0xbfb8aa3b, v31
	v_exp_f32_e32 v38, v38
	v_exp_f32_e32 v39, v39
	v_cvt_pk_bf16_f32 v35, v40, v41
	v_cvt_pk_bf16_f32 v36, v42, v43
	v_cvt_pk_bf16_f32 v37, v44, v45
	global_store_dwordx4 v[46:47], v[34:37], off nt
	s_nop 1
	v_add_f32_e32 v34, 1.0, v38
	v_add_f32_e32 v35, 1.0, v39
	v_rcp_f32_e32 v34, v34
	v_rcp_f32_e32 v35, v35
	v_add_u32_e32 v36, 0xa0, v153
	v_mad_i64_i32 v[36:37], s[20:21], v36, s50, v[146:147]
	v_pk_mul_f32 v[30:31], v[30:31], v[34:35]
	v_mul_f32_e32 v34, 0xbfb8aa3b, v32
	v_mul_f32_e32 v35, 0xbfb8aa3b, v33
	v_exp_f32_e32 v34, v34
	v_exp_f32_e32 v35, v35
	v_pk_mul_f32 v[22:23], v[30:31], v[22:23]
	v_add_f32_e32 v30, 1.0, v34
	v_add_f32_e32 v31, 1.0, v35
	v_mul_f32_e32 v34, 0xbfb8aa3b, v26
	v_mul_f32_e32 v35, 0xbfb8aa3b, v27
	v_rcp_f32_e32 v30, v30
	v_rcp_f32_e32 v31, v31
	v_exp_f32_e32 v34, v34
	v_exp_f32_e32 v35, v35
	v_pk_mul_f32 v[30:31], v[32:33], v[30:31]
	v_add_f32_e32 v32, 1.0, v34
	v_add_f32_e32 v33, 1.0, v35
	v_mul_f32_e32 v34, 0xbfb8aa3b, v28
	v_mul_f32_e32 v35, 0xbfb8aa3b, v29
	v_exp_f32_e32 v34, v34
	v_exp_f32_e32 v35, v35
	v_rcp_f32_e32 v32, v32
	v_rcp_f32_e32 v33, v33
	v_add_f32_e32 v34, 1.0, v34
	v_add_f32_e32 v35, 1.0, v35
	v_rcp_f32_e32 v34, v34
	v_rcp_f32_e32 v35, v35
	v_pk_mul_f32 v[26:27], v[26:27], v[32:33]
	v_pk_mul_f32 v[24:25], v[30:31], v[24:25]
	v_pk_mul_f32 v[26:27], v[26:27], v[18:19]
	v_pk_mul_f32 v[18:19], v[28:29], v[34:35]
	v_lshl_add_u64 v[30:31], v[36:37], 0, v[114:115]
	v_pk_mul_f32 v[28:29], v[18:19], v[20:21]
	v_cvt_pk_bf16_f32 v18, v22, v23
	v_mul_f32_e32 v22, 0xbfb8aa3b, v14
	v_mul_f32_e32 v23, 0xbfb8aa3b, v15
	v_exp_f32_e32 v22, v22
	v_exp_f32_e32 v23, v23
	v_cvt_pk_bf16_f32 v19, v24, v25
	v_cvt_pk_bf16_f32 v20, v26, v27
	v_cvt_pk_bf16_f32 v21, v28, v29
	global_store_dwordx4 v[30:31], v[18:21], off nt
	s_nop 1
	v_add_f32_e32 v18, 1.0, v22
	v_add_f32_e32 v19, 1.0, v23
	v_rcp_f32_e32 v18, v18
	v_rcp_f32_e32 v19, v19
	v_add_u32_e32 v20, 0xb0, v153
	v_mad_i64_i32 v[20:21], s[20:21], v20, s50, v[146:147]
	v_pk_mul_f32 v[14:15], v[14:15], v[18:19]
	v_mul_f32_e32 v18, 0xbfb8aa3b, v16
	v_mul_f32_e32 v19, 0xbfb8aa3b, v17
	v_exp_f32_e32 v18, v18
	v_exp_f32_e32 v19, v19
	v_pk_mul_f32 v[6:7], v[14:15], v[6:7]
	v_add_f32_e32 v14, 1.0, v18
	v_add_f32_e32 v15, 1.0, v19
	v_mul_f32_e32 v18, 0xbfb8aa3b, v10
	v_mul_f32_e32 v19, 0xbfb8aa3b, v11
	v_rcp_f32_e32 v14, v14
	v_rcp_f32_e32 v15, v15
	v_exp_f32_e32 v18, v18
	v_exp_f32_e32 v19, v19
	v_pk_mul_f32 v[14:15], v[16:17], v[14:15]
	v_add_f32_e32 v16, 1.0, v18
	v_add_f32_e32 v17, 1.0, v19
	v_mul_f32_e32 v18, 0xbfb8aa3b, v12
	v_mul_f32_e32 v19, 0xbfb8aa3b, v13
	v_exp_f32_e32 v18, v18
	v_exp_f32_e32 v19, v19
	v_rcp_f32_e32 v16, v16
	v_rcp_f32_e32 v17, v17
	v_add_f32_e32 v18, 1.0, v18
	v_add_f32_e32 v19, 1.0, v19
	v_rcp_f32_e32 v18, v18
	v_rcp_f32_e32 v19, v19
	v_pk_mul_f32 v[10:11], v[10:11], v[16:17]
	v_pk_mul_f32 v[8:9], v[14:15], v[8:9]
	v_pk_mul_f32 v[10:11], v[10:11], v[2:3]
	v_pk_mul_f32 v[2:3], v[12:13], v[18:19]
	v_lshl_add_u64 v[14:15], v[20:21], 0, v[114:115]
	v_pk_mul_f32 v[12:13], v[2:3], v[4:5]
	v_cvt_pk_bf16_f32 v2, v6, v7
	v_cvt_pk_bf16_f32 v3, v8, v9
	v_cvt_pk_bf16_f32 v4, v10, v11
	v_cvt_pk_bf16_f32 v5, v12, v13
	global_store_dwordx4 v[14:15], v[2:5], off nt
	s_cbranch_vccnz .LBB0_82
	s_andn2_b64 vcc, exec, s[8:9]
	s_cbranch_vccnz .LBB0_81
	s_barrier
	s_branch .LBB0_81

.LBB0_648:
	v_mul_f32_e32 v146, 0xbfb8aa3b, v126
	v_exp_f32_e32 v146, v146
	v_mul_f32_e32 v147, 0xbfb8aa3b, v127
	v_exp_f32_e32 v147, v147
	v_lshl_or_b32 v154, s51, 7, v149
	v_add_f32_e32 v146, 1.0, v146
	v_rcp_f32_e32 v156, v146
	v_add_f32_e32 v146, 1.0, v147
	v_rcp_f32_e32 v157, v146
	v_lshl_add_u32 v153, s24, 8, v1
	v_ashrrev_i32_e32 v155, 31, v154
	v_mov_b64_e32 v[146:147], s[6:7]
	v_pk_mul_f32 v[126:127], v[126:127], v[156:157]
	v_mul_f32_e32 v156, 0xbfb8aa3b, v128
	v_mul_f32_e32 v157, 0xbfb8aa3b, v129
	v_exp_f32_e32 v156, v156
	v_exp_f32_e32 v157, v157
	v_pk_mul_f32 v[118:119], v[126:127], v[118:119]
	v_mad_i64_i32 v[158:159], s[20:21], v153, s50, v[146:147]
	v_add_f32_e32 v126, 1.0, v156
	v_add_f32_e32 v127, 1.0, v157
	v_mul_f32_e32 v156, 0xbfb8aa3b, v122
	v_mul_f32_e32 v157, 0xbfb8aa3b, v123
	v_rcp_f32_e32 v126, v126
	v_rcp_f32_e32 v127, v127
	v_exp_f32_e32 v156, v156
	v_exp_f32_e32 v157, v157
	s_andn2_b64 vcc, exec, s[2:3]
	v_pk_mul_f32 v[126:127], v[128:129], v[126:127]
	v_add_f32_e32 v128, 1.0, v156
	v_add_f32_e32 v129, 1.0, v157
	v_mul_f32_e32 v156, 0xbfb8aa3b, v124
	v_mul_f32_e32 v157, 0xbfb8aa3b, v125
	v_exp_f32_e32 v156, v156
	v_exp_f32_e32 v157, v157
	v_rcp_f32_e32 v128, v128
	v_rcp_f32_e32 v129, v129
	v_add_f32_e32 v156, 1.0, v156
	v_add_f32_e32 v157, 1.0, v157
	v_rcp_f32_e32 v156, v156
	v_rcp_f32_e32 v157, v157
	v_pk_mul_f32 v[122:123], v[122:123], v[128:129]
	v_pk_mul_f32 v[120:121], v[126:127], v[120:121]
	v_pk_mul_f32 v[122:123], v[122:123], v[114:115]
	v_pk_mul_f32 v[114:115], v[124:125], v[156:157]
	s_mov_b64 s[2:3], -1
	v_pk_mul_f32 v[124:125], v[114:115], v[116:117]
	v_cvt_pk_bf16_f32 v117, v120, v121
	v_mul_f32_e32 v120, 0xbfb8aa3b, v110
	v_mul_f32_e32 v121, 0xbfb8aa3b, v111
	v_exp_f32_e32 v120, v120
	v_exp_f32_e32 v121, v121
	v_lshlrev_b64 v[114:115], 1, v[154:155]
	v_lshl_add_u64 v[126:127], v[158:159], 0, v[114:115]
	v_cvt_pk_bf16_f32 v116, v118, v119
	v_cvt_pk_bf16_f32 v118, v122, v123
	v_cvt_pk_bf16_f32 v119, v124, v125
	global_store_dwordx4 v[126:127], v[116:119], off nt
	s_nop 1
	v_add_f32_e32 v116, 1.0, v120
	v_add_f32_e32 v117, 1.0, v121
	v_rcp_f32_e32 v116, v116
	v_rcp_f32_e32 v117, v117
	v_or_b32_e32 v118, 16, v153
	v_mad_i64_i32 v[118:119], s[20:21], v118, s50, v[146:147]
	v_pk_mul_f32 v[110:111], v[110:111], v[116:117]
	v_mul_f32_e32 v116, 0xbfb8aa3b, v112
	v_mul_f32_e32 v117, 0xbfb8aa3b, v113
	v_exp_f32_e32 v116, v116
	v_exp_f32_e32 v117, v117
	v_pk_mul_f32 v[102:103], v[110:111], v[102:103]
	v_add_f32_e32 v110, 1.0, v116
	v_add_f32_e32 v111, 1.0, v117
	v_mul_f32_e32 v116, 0xbfb8aa3b, v106
	v_mul_f32_e32 v117, 0xbfb8aa3b, v107
	v_rcp_f32_e32 v110, v110
	v_rcp_f32_e32 v111, v111
	v_exp_f32_e32 v116, v116
	v_exp_f32_e32 v117, v117
	v_pk_mul_f32 v[110:111], v[112:113], v[110:111]
	v_add_f32_e32 v112, 1.0, v116
	v_add_f32_e32 v113, 1.0, v117
	v_mul_f32_e32 v116, 0xbfb8aa3b, v108
	v_mul_f32_e32 v117, 0xbfb8aa3b, v109
	v_exp_f32_e32 v116, v116
	v_exp_f32_e32 v117, v117
	v_rcp_f32_e32 v112, v112
	v_rcp_f32_e32 v113, v113
	v_add_f32_e32 v116, 1.0, v116
	v_add_f32_e32 v117, 1.0, v117
	v_rcp_f32_e32 v116, v116
	v_rcp_f32_e32 v117, v117
	v_pk_mul_f32 v[106:107], v[106:107], v[112:113]
	v_pk_mul_f32 v[104:105], v[110:111], v[104:105]
	v_pk_mul_f32 v[106:107], v[106:107], v[98:99]
	v_pk_mul_f32 v[98:99], v[108:109], v[116:117]
	v_lshl_add_u64 v[110:111], v[118:119], 0, v[114:115]
	v_pk_mul_f32 v[108:109], v[98:99], v[100:101]
	v_cvt_pk_bf16_f32 v98, v102, v103
	v_mul_f32_e32 v102, 0xbfb8aa3b, v94
	v_mul_f32_e32 v103, 0xbfb8aa3b, v95
	v_exp_f32_e32 v102, v102
	v_exp_f32_e32 v103, v103
	v_cvt_pk_bf16_f32 v99, v104, v105
	v_cvt_pk_bf16_f32 v100, v106, v107
	v_cvt_pk_bf16_f32 v101, v108, v109
	global_store_dwordx4 v[110:111], v[98:101], off nt
	s_nop 1
	v_add_f32_e32 v98, 1.0, v102
	v_add_f32_e32 v99, 1.0, v103
	v_rcp_f32_e32 v98, v98
	v_rcp_f32_e32 v99, v99
	v_or_b32_e32 v100, 32, v153
	v_mad_i64_i32 v[100:101], s[20:21], v100, s50, v[146:147]
	v_pk_mul_f32 v[94:95], v[94:95], v[98:99]
	v_mul_f32_e32 v98, 0xbfb8aa3b, v96
	v_mul_f32_e32 v99, 0xbfb8aa3b, v97
	v_exp_f32_e32 v98, v98
	v_exp_f32_e32 v99, v99
	v_pk_mul_f32 v[86:87], v[94:95], v[86:87]
	v_add_f32_e32 v94, 1.0, v98
	v_add_f32_e32 v95, 1.0, v99
	v_mul_f32_e32 v98, 0xbfb8aa3b, v90
	v_mul_f32_e32 v99, 0xbfb8aa3b, v91
	v_rcp_f32_e32 v94, v94
	v_rcp_f32_e32 v95, v95
	v_exp_f32_e32 v98, v98
	v_exp_f32_e32 v99, v99
	v_pk_mul_f32 v[94:95], v[96:97], v[94:95]
	v_add_f32_e32 v96, 1.0, v98
	v_add_f32_e32 v97, 1.0, v99
	v_mul_f32_e32 v98, 0xbfb8aa3b, v92
	v_mul_f32_e32 v99, 0xbfb8aa3b, v93
	v_exp_f32_e32 v98, v98
	v_exp_f32_e32 v99, v99
	v_rcp_f32_e32 v96, v96
	v_rcp_f32_e32 v97, v97
	v_add_f32_e32 v98, 1.0, v98
	v_add_f32_e32 v99, 1.0, v99
	v_rcp_f32_e32 v98, v98
	v_rcp_f32_e32 v99, v99
	v_pk_mul_f32 v[90:91], v[90:91], v[96:97]
	v_pk_mul_f32 v[88:89], v[94:95], v[88:89]
	v_pk_mul_f32 v[90:91], v[90:91], v[82:83]
	v_pk_mul_f32 v[82:83], v[92:93], v[98:99]
	v_lshl_add_u64 v[94:95], v[100:101], 0, v[114:115]
	v_pk_mul_f32 v[92:93], v[82:83], v[84:85]
	v_cvt_pk_bf16_f32 v82, v86, v87
	v_mul_f32_e32 v86, 0xbfb8aa3b, v78
	v_mul_f32_e32 v87, 0xbfb8aa3b, v79
	v_exp_f32_e32 v86, v86
	v_exp_f32_e32 v87, v87
	v_cvt_pk_bf16_f32 v83, v88, v89
	v_cvt_pk_bf16_f32 v84, v90, v91
	v_cvt_pk_bf16_f32 v85, v92, v93
	global_store_dwordx4 v[94:95], v[82:85], off nt
	s_nop 1
	v_add_f32_e32 v82, 1.0, v86
	v_add_f32_e32 v83, 1.0, v87
	v_rcp_f32_e32 v82, v82
	v_rcp_f32_e32 v83, v83
	v_or_b32_e32 v84, 48, v153
	v_mad_i64_i32 v[84:85], s[20:21], v84, s50, v[146:147]
	v_pk_mul_f32 v[78:79], v[78:79], v[82:83]
	v_mul_f32_e32 v82, 0xbfb8aa3b, v80
	v_mul_f32_e32 v83, 0xbfb8aa3b, v81
	v_exp_f32_e32 v82, v82
	v_exp_f32_e32 v83, v83
	v_pk_mul_f32 v[70:71], v[78:79], v[70:71]
	v_add_f32_e32 v78, 1.0, v82
	v_add_f32_e32 v79, 1.0, v83
	v_mul_f32_e32 v82, 0xbfb8aa3b, v74
	v_mul_f32_e32 v83, 0xbfb8aa3b, v75
	v_rcp_f32_e32 v78, v78
	v_rcp_f32_e32 v79, v79
	v_exp_f32_e32 v82, v82
	v_exp_f32_e32 v83, v83
	v_pk_mul_f32 v[78:79], v[80:81], v[78:79]
	v_add_f32_e32 v80, 1.0, v82
	v_add_f32_e32 v81, 1.0, v83
	v_mul_f32_e32 v82, 0xbfb8aa3b, v76
	v_mul_f32_e32 v83, 0xbfb8aa3b, v77
	v_exp_f32_e32 v82, v82
	v_exp_f32_e32 v83, v83
	v_rcp_f32_e32 v80, v80
	v_rcp_f32_e32 v81, v81
	v_add_f32_e32 v82, 1.0, v82
	v_add_f32_e32 v83, 1.0, v83
	v_rcp_f32_e32 v82, v82
	v_rcp_f32_e32 v83, v83
	v_pk_mul_f32 v[74:75], v[74:75], v[80:81]
	v_pk_mul_f32 v[72:73], v[78:79], v[72:73]
	v_pk_mul_f32 v[74:75], v[74:75], v[66:67]
	v_pk_mul_f32 v[66:67], v[76:77], v[82:83]
	v_lshl_add_u64 v[78:79], v[84:85], 0, v[114:115]
	v_pk_mul_f32 v[76:77], v[66:67], v[68:69]
	v_cvt_pk_bf16_f32 v66, v70, v71
	v_mul_f32_e32 v70, 0xbfb8aa3b, v62
	v_mul_f32_e32 v71, 0xbfb8aa3b, v63
	v_exp_f32_e32 v70, v70
	v_exp_f32_e32 v71, v71
	v_cvt_pk_bf16_f32 v67, v72, v73
	v_cvt_pk_bf16_f32 v68, v74, v75
	v_cvt_pk_bf16_f32 v69, v76, v77
	global_store_dwordx4 v[78:79], v[66:69], off nt
	s_nop 1
	v_add_f32_e32 v66, 1.0, v70
	v_add_f32_e32 v67, 1.0, v71
	v_rcp_f32_e32 v66, v66
	v_rcp_f32_e32 v67, v67
	v_add_u32_e32 v68, 0x80, v153
	v_mad_i64_i32 v[68:69], s[20:21], v68, s50, v[146:147]
	v_pk_mul_f32 v[62:63], v[62:63], v[66:67]
	v_mul_f32_e32 v66, 0xbfb8aa3b, v64
	v_mul_f32_e32 v67, 0xbfb8aa3b, v65
	v_exp_f32_e32 v66, v66
	v_exp_f32_e32 v67, v67
	v_pk_mul_f32 v[54:55], v[62:63], v[54:55]
	v_add_f32_e32 v62, 1.0, v66
	v_add_f32_e32 v63, 1.0, v67
	v_mul_f32_e32 v66, 0xbfb8aa3b, v58
	v_mul_f32_e32 v67, 0xbfb8aa3b, v59
	v_rcp_f32_e32 v62, v62
	v_rcp_f32_e32 v63, v63
	v_exp_f32_e32 v66, v66
	v_exp_f32_e32 v67, v67
	v_pk_mul_f32 v[62:63], v[64:65], v[62:63]
	v_add_f32_e32 v64, 1.0, v66
	v_add_f32_e32 v65, 1.0, v67
	v_mul_f32_e32 v66, 0xbfb8aa3b, v60
	v_mul_f32_e32 v67, 0xbfb8aa3b, v61
	v_exp_f32_e32 v66, v66
	v_exp_f32_e32 v67, v67
	v_rcp_f32_e32 v64, v64
	v_rcp_f32_e32 v65, v65
	v_add_f32_e32 v66, 1.0, v66
	v_add_f32_e32 v67, 1.0, v67
	v_rcp_f32_e32 v66, v66
	v_rcp_f32_e32 v67, v67
	v_pk_mul_f32 v[58:59], v[58:59], v[64:65]
	v_pk_mul_f32 v[56:57], v[62:63], v[56:57]
	v_pk_mul_f32 v[58:59], v[58:59], v[50:51]
	v_pk_mul_f32 v[50:51], v[60:61], v[66:67]
	v_lshl_add_u64 v[62:63], v[68:69], 0, v[114:115]
	v_pk_mul_f32 v[60:61], v[50:51], v[52:53]
	v_cvt_pk_bf16_f32 v50, v54, v55
	v_mul_f32_e32 v54, 0xbfb8aa3b, v46
	v_mul_f32_e32 v55, 0xbfb8aa3b, v47
	v_exp_f32_e32 v54, v54
	v_exp_f32_e32 v55, v55
	v_cvt_pk_bf16_f32 v51, v56, v57
	v_cvt_pk_bf16_f32 v52, v58, v59
	v_cvt_pk_bf16_f32 v53, v60, v61
	global_store_dwordx4 v[62:63], v[50:53], off nt
	s_nop 1
	v_add_f32_e32 v50, 1.0, v54
	v_add_f32_e32 v51, 1.0, v55
	v_rcp_f32_e32 v50, v50
	v_rcp_f32_e32 v51, v51
	v_add_u32_e32 v52, 0x90, v153
	v_mad_i64_i32 v[52:53], s[20:21], v52, s50, v[146:147]
	v_pk_mul_f32 v[46:47], v[46:47], v[50:51]
	v_mul_f32_e32 v50, 0xbfb8aa3b, v48
	v_mul_f32_e32 v51, 0xbfb8aa3b, v49
	v_exp_f32_e32 v50, v50
	v_exp_f32_e32 v51, v51
	v_pk_mul_f32 v[38:39], v[46:47], v[38:39]
	v_add_f32_e32 v46, 1.0, v50
	v_add_f32_e32 v47, 1.0, v51
	v_mul_f32_e32 v50, 0xbfb8aa3b, v42
	v_mul_f32_e32 v51, 0xbfb8aa3b, v43
	v_rcp_f32_e32 v46, v46
	v_rcp_f32_e32 v47, v47
	v_exp_f32_e32 v50, v50
	v_exp_f32_e32 v51, v51
	v_pk_mul_f32 v[46:47], v[48:49], v[46:47]
	v_add_f32_e32 v48, 1.0, v50
	v_add_f32_e32 v49, 1.0, v51
	v_mul_f32_e32 v50, 0xbfb8aa3b, v44
	v_mul_f32_e32 v51, 0xbfb8aa3b, v45
	v_exp_f32_e32 v50, v50
	v_exp_f32_e32 v51, v51
	v_rcp_f32_e32 v48, v48
	v_rcp_f32_e32 v49, v49
	v_add_f32_e32 v50, 1.0, v50
	v_add_f32_e32 v51, 1.0, v51
	v_rcp_f32_e32 v50, v50
	v_rcp_f32_e32 v51, v51
	v_pk_mul_f32 v[42:43], v[42:43], v[48:49]
	v_pk_mul_f32 v[40:41], v[46:47], v[40:41]
	v_pk_mul_f32 v[42:43], v[42:43], v[34:35]
	v_pk_mul_f32 v[34:35], v[44:45], v[50:51]
	v_lshl_add_u64 v[46:47], v[52:53], 0, v[114:115]
	v_pk_mul_f32 v[44:45], v[34:35], v[36:37]
	v_cvt_pk_bf16_f32 v34, v38, v39
	v_mul_f32_e32 v38, 0xbfb8aa3b, v30
	v_mul_f32_e32 v39, 0xbfb8aa3b, v31
	v_exp_f32_e32 v38, v38
	v_exp_f32_e32 v39, v39
	v_cvt_pk_bf16_f32 v35, v40, v41
	v_cvt_pk_bf16_f32 v36, v42, v43
	v_cvt_pk_bf16_f32 v37, v44, v45
	global_store_dwordx4 v[46:47], v[34:37], off nt
	s_nop 1
	v_add_f32_e32 v34, 1.0, v38
	v_add_f32_e32 v35, 1.0, v39
	v_rcp_f32_e32 v34, v34
	v_rcp_f32_e32 v35, v35
	v_add_u32_e32 v36, 0xa0, v153
	v_mad_i64_i32 v[36:37], s[20:21], v36, s50, v[146:147]
	v_pk_mul_f32 v[30:31], v[30:31], v[34:35]
	v_mul_f32_e32 v34, 0xbfb8aa3b, v32
	v_mul_f32_e32 v35, 0xbfb8aa3b, v33
	v_exp_f32_e32 v34, v34
	v_exp_f32_e32 v35, v35
	v_pk_mul_f32 v[22:23], v[30:31], v[22:23]
	v_add_f32_e32 v30, 1.0, v34
	v_add_f32_e32 v31, 1.0, v35
	v_mul_f32_e32 v34, 0xbfb8aa3b, v26
	v_mul_f32_e32 v35, 0xbfb8aa3b, v27
	v_rcp_f32_e32 v30, v30
	v_rcp_f32_e32 v31, v31
	v_exp_f32_e32 v34, v34
	v_exp_f32_e32 v35, v35
	v_pk_mul_f32 v[30:31], v[32:33], v[30:31]
	v_add_f32_e32 v32, 1.0, v34
	v_add_f32_e32 v33, 1.0, v35
	v_mul_f32_e32 v34, 0xbfb8aa3b, v28
	v_mul_f32_e32 v35, 0xbfb8aa3b, v29
	v_exp_f32_e32 v34, v34
	v_exp_f32_e32 v35, v35
	v_rcp_f32_e32 v32, v32
	v_rcp_f32_e32 v33, v33
	v_add_f32_e32 v34, 1.0, v34
	v_add_f32_e32 v35, 1.0, v35
	v_rcp_f32_e32 v34, v34
	v_rcp_f32_e32 v35, v35
	v_pk_mul_f32 v[26:27], v[26:27], v[32:33]
	v_pk_mul_f32 v[24:25], v[30:31], v[24:25]
	v_pk_mul_f32 v[26:27], v[26:27], v[18:19]
	v_pk_mul_f32 v[18:19], v[28:29], v[34:35]
	v_lshl_add_u64 v[30:31], v[36:37], 0, v[114:115]
	v_pk_mul_f32 v[28:29], v[18:19], v[20:21]
	v_cvt_pk_bf16_f32 v18, v22, v23
	v_mul_f32_e32 v22, 0xbfb8aa3b, v14
	v_mul_f32_e32 v23, 0xbfb8aa3b, v15
	v_exp_f32_e32 v22, v22
	v_exp_f32_e32 v23, v23
	v_cvt_pk_bf16_f32 v19, v24, v25
	v_cvt_pk_bf16_f32 v20, v26, v27
	v_cvt_pk_bf16_f32 v21, v28, v29
	global_store_dwordx4 v[30:31], v[18:21], off nt
	s_nop 1
	v_add_f32_e32 v18, 1.0, v22
	v_add_f32_e32 v19, 1.0, v23
	v_rcp_f32_e32 v18, v18
	v_rcp_f32_e32 v19, v19
	v_add_u32_e32 v20, 0xb0, v153
	v_mad_i64_i32 v[20:21], s[20:21], v20, s50, v[146:147]
	v_pk_mul_f32 v[14:15], v[14:15], v[18:19]
	v_mul_f32_e32 v18, 0xbfb8aa3b, v16
	v_mul_f32_e32 v19, 0xbfb8aa3b, v17
	v_exp_f32_e32 v18, v18
	v_exp_f32_e32 v19, v19
	v_pk_mul_f32 v[6:7], v[14:15], v[6:7]
	v_add_f32_e32 v14, 1.0, v18
	v_add_f32_e32 v15, 1.0, v19
	v_mul_f32_e32 v18, 0xbfb8aa3b, v10
	v_mul_f32_e32 v19, 0xbfb8aa3b, v11
	v_rcp_f32_e32 v14, v14
	v_rcp_f32_e32 v15, v15
	v_exp_f32_e32 v18, v18
	v_exp_f32_e32 v19, v19
	v_pk_mul_f32 v[14:15], v[16:17], v[14:15]
	v_add_f32_e32 v16, 1.0, v18
	v_add_f32_e32 v17, 1.0, v19
	v_mul_f32_e32 v18, 0xbfb8aa3b, v12
	v_mul_f32_e32 v19, 0xbfb8aa3b, v13
	v_exp_f32_e32 v18, v18
	v_exp_f32_e32 v19, v19
	v_rcp_f32_e32 v16, v16
	v_rcp_f32_e32 v17, v17
	v_add_f32_e32 v18, 1.0, v18
	v_add_f32_e32 v19, 1.0, v19
	v_rcp_f32_e32 v18, v18
	v_rcp_f32_e32 v19, v19
	v_pk_mul_f32 v[10:11], v[10:11], v[16:17]
	v_pk_mul_f32 v[8:9], v[14:15], v[8:9]
	v_pk_mul_f32 v[10:11], v[10:11], v[2:3]
	v_pk_mul_f32 v[2:3], v[12:13], v[18:19]
	v_lshl_add_u64 v[14:15], v[20:21], 0, v[114:115]
	v_pk_mul_f32 v[12:13], v[2:3], v[4:5]
	v_cvt_pk_bf16_f32 v2, v6, v7
	v_cvt_pk_bf16_f32 v3, v8, v9
	v_cvt_pk_bf16_f32 v4, v10, v11
	v_cvt_pk_bf16_f32 v5, v12, v13
	global_store_dwordx4 v[14:15], v[2:5], off nt
	s_cbranch_vccnz .LBB0_641
	s_andn2_b64 vcc, exec, s[4:5]
	s_cbranch_vccnz .LBB0_640
	s_barrier
	s_branch .LBB0_640
